# v15 plus D-loop early-exit flag check: 8 serialized flat LDS loads replaced by 2 ds_read_b128
# baseline (speedup 1.0000x reference)
; template <int MODE>
; DI void attn_unit(unsigned char* lds, const AttnParams& ap, int b, int h, int qb, int tid) {
;     ...
;     const int jb = (MODE == 2) ? jhi - n : jlo + n;
;     __syncthreads();
;     if (MODE == 2 && D_EARLY) { int alld = 1;
; #pragma unroll
;       for (int w = 0; w < 8; ++w) alld &= flags[w];
;       if (alld) break; }
; #pragma unroll
;     for (int c = 0; c < NCH; ++c) { *(u32x4*)(Ks0 + (c * 64 + lrow) * 72 + 8 * lch) = kreg[c]; *(u32x4*)(Vs0 + (c * 64 + lrow) * 72 + 8 * lch) = vreg[c]; }
;     __syncthreads();
;     if (n + NCH < ntiles) {
; #pragma unroll
;       for (int c = 0; c < NCH; ++c) { const int jn = (MODE == 2) ? jb - NCH - c : jb + NCH + c; kreg[c] = *(const u32x4*)(kg + (size_t)jn * 64 * PLD); vreg[c] = *(const u32x4*)(vg + (size_t)jn * 4096); } }
.LBB0_833:
	v_mov_b32_e32 v0, 0x4800
	v_mov_b32_e32 v4, 0x4810
	s_waitcnt lgkmcnt(0)
	s_barrier
	ds_read_b128 v[0:3], v0
	ds_read_b128 v[4:7], v4
	s_or_b64 s[78:79], s[78:79], exec
	s_waitcnt vmcnt(0) lgkmcnt(0)
	v_bitop3_b32 v0, v0, v1, v2 bitop3:0x80
	v_bitop3_b32 v4, v4, v5, v6 bitop3:0x80
	v_bitop3_b32 v0, v0, v3, v7 bitop3:0x80
	v_bitop3_b32 v0, v0, 1, v4 bitop3:0x80
	v_cmp_eq_u32_e64 s[8:9], 0, v0
	s_and_saveexec_b64 s[94:95], s[8:9]
	s_cbranch_execz .LBB0_832
	v_cmp_lt_u32_e64 s[8:9], s88, v157
	ds_write_b128 v170, v[144:147]
	ds_write_b128 v170, v[148:151] offset:9216
	s_waitcnt lgkmcnt(0)
	s_barrier
	s_and_saveexec_b64 s[4:5], s[8:9]
	s_cbranch_execz .LBB0_836
	global_load_dwordx4 v[144:147], v[166:167], off
	global_load_dwordx4 v[148:151], v[164:165], off
